# context sequences: forward scan stores y (no atomics), backward scan of the same sequence accumulates; on top of previous edits
# speedup vs baseline: 1.1094x; 1.0019x over previous
.LBB0_1213:
	s_or_b64 exec, exec, s[58:59]
	v_ashrrev_i32_e32 v35, 4, v141
	v_mul_lo_u32 v50, v35, s78
	v_lshlrev_b32_e32 v52, 2, v34
	s_waitcnt lgkmcnt(0)
	s_barrier
	v_add_u32_e32 v36, 0x3100, v50
	v_add_u32_e32 v48, 0x2000, v52
	ds_read2_b32 v[36:37], v36 offset1:1
	ds_read2_b32 v[38:39], v48 offset0:48 offset1:81
	v_add_u32_e32 v40, 0x3108, v50
	v_add_u32_e32 v42, 0x3110, v50
	v_add_u32_e32 v44, 0x3118, v50
	ds_read2_b32 v[40:41], v40 offset1:1
	ds_read2_b32 v[42:43], v42 offset1:1
	ds_read2_b32 v[44:45], v44 offset1:1
	ds_read2_b32 v[46:47], v48 offset0:114 offset1:147
	s_waitcnt lgkmcnt(4)
	v_fma_f32 v49, v36, v38, 0
	v_fmac_f32_e32 v49, v37, v39
	ds_read2_b32 v[36:37], v48 offset0:180 offset1:213
	v_add_u32_e32 v38, 0x2200, v52
	ds_read2_b32 v[38:39], v38 offset0:118 offset1:151
	s_waitcnt lgkmcnt(2)
	v_fmac_f32_e32 v49, v40, v46
	v_fmac_f32_e32 v49, v41, v47
	s_waitcnt lgkmcnt(1)
	v_fmac_f32_e32 v49, v42, v36
	v_fmac_f32_e32 v49, v43, v37
	s_waitcnt lgkmcnt(0)
	v_fmac_f32_e32 v49, v44, v38
	v_add_u32_e32 v36, 0x3120, v50
	v_add_u32_e32 v48, 0x2400, v52
	v_fmac_f32_e32 v49, v45, v39
	ds_read2_b32 v[36:37], v36 offset1:1
	ds_read2_b32 v[38:39], v48 offset0:56 offset1:89
	v_add_u32_e32 v40, 0x3128, v50
	v_add_u32_e32 v42, 0x3130, v50
	v_add_u32_e32 v44, 0x3138, v50
	ds_read2_b32 v[40:41], v40 offset1:1
	ds_read2_b32 v[42:43], v42 offset1:1
	ds_read2_b32 v[44:45], v44 offset1:1
	ds_read2_b32 v[46:47], v48 offset0:122 offset1:155
	s_waitcnt lgkmcnt(4)
	v_fmac_f32_e32 v49, v36, v38
	v_fmac_f32_e32 v49, v37, v39
	ds_read2_b32 v[36:37], v48 offset0:188 offset1:221
	v_add_u32_e32 v38, 0x2600, v52
	ds_read2_b32 v[38:39], v38 offset0:126 offset1:159
	s_waitcnt lgkmcnt(2)
	v_fmac_f32_e32 v49, v40, v46
	v_fmac_f32_e32 v49, v41, v47
	s_waitcnt lgkmcnt(1)
	v_fmac_f32_e32 v49, v42, v36
	v_fmac_f32_e32 v49, v43, v37
	s_waitcnt lgkmcnt(0)
	v_fmac_f32_e32 v49, v44, v38
	v_fmac_f32_e32 v49, v45, v39
	v_add_u32_e32 v37, v50, v52
	ds_write_b32 v37, v49 offset:14720
	v_mul_lo_u32 v37, v35, s77
	v_lshl_add_u32 v37, v34, 1, v37
	ds_write_b16 v37, v1 offset:58336
	v_add_u32_e32 v36, 0x3980, v50
	s_waitcnt lgkmcnt(0)
	s_barrier
	v_add_u32_e32 v53, 0x3400, v52
	ds_read2_b32 v[36:37], v36 offset1:1
	ds_read2_b32 v[38:39], v53 offset0:80 offset1:97
	ds_read2_b32 v[40:41], v53 offset0:114 offset1:131
	v_add_u32_e32 v42, 0x3988, v50
	v_add_u32_e32 v44, 0x3990, v50
	v_add_u32_e32 v46, 0x3998, v50
	ds_read2_b32 v[42:43], v42 offset1:1
	ds_read2_b32 v[44:45], v44 offset1:1
	ds_read2_b32 v[46:47], v46 offset1:1
	ds_read2_b32 v[48:49], v53 offset0:148 offset1:165
	s_waitcnt lgkmcnt(5)
	v_fma_f32 v54, v36, v38, 0
	v_fmac_f32_e32 v54, v37, v39
	ds_read2_b32 v[36:37], v53 offset0:182 offset1:199
	s_waitcnt lgkmcnt(4)
	v_fmac_f32_e32 v54, v42, v40
	v_fmac_f32_e32 v54, v43, v41
	s_waitcnt lgkmcnt(1)
	v_fmac_f32_e32 v54, v44, v48
	v_fmac_f32_e32 v54, v45, v49
	s_waitcnt lgkmcnt(0)
	v_fmac_f32_e32 v54, v46, v36
	v_add_u32_e32 v36, 0x39a0, v50
	v_fmac_f32_e32 v54, v47, v37
	ds_read2_b32 v[36:37], v36 offset1:1
	ds_read2_b32 v[38:39], v53 offset0:216 offset1:233
	v_add_u32_e32 v40, 0x39a8, v50
	v_add_u32_e32 v42, 0x39b0, v50
	v_add_u32_e32 v44, 0x39b8, v50
	ds_read2_b32 v[40:41], v40 offset1:1
	ds_read2_b32 v[42:43], v42 offset1:1
	ds_read2_b32 v[44:45], v44 offset1:1
	s_waitcnt lgkmcnt(3)
	v_fmac_f32_e32 v54, v36, v38
	v_add_u32_e32 v36, 0x3600, v52
	ds_read2_b32 v[46:47], v36 offset0:122 offset1:139
	v_add_u32_e32 v36, 0x3800, v52
	ds_read2_b32 v[48:49], v36 offset0:28 offset1:45
	v_fmac_f32_e32 v54, v37, v39
	ds_read2_b32 v[36:37], v36 offset0:62 offset1:79
	s_waitcnt lgkmcnt(2)
	v_fmac_f32_e32 v54, v40, v46
	v_fmac_f32_e32 v54, v41, v47
	s_waitcnt lgkmcnt(1)
	v_fmac_f32_e32 v54, v42, v48
	v_fmac_f32_e32 v54, v43, v49
	s_waitcnt lgkmcnt(0)
	v_fmac_f32_e32 v54, v44, v36
	v_fmac_f32_e32 v54, v45, v37
	v_lshlrev_b32_e32 v35, 1, v35
	v_cvt_pk_bf16_f32 v36, v54, s0
	v_mad_u32_u24 v34, v34, s77, v35
	ds_write_b16 v34, v36 offset:59584
	s_waitcnt lgkmcnt(0)
	s_barrier
	s_andn2_b64 vcc, exec, s[8:9]
	s_cbranch_vccnz .LBB0_1106
	v_lshlrev_b32_e32 v80, 1, v0
	v_add_u32_e32 v46, v66, v80
	v_add_u32_e32 v47, 0x4000, v46
	ds_read2_b64 v[34:37], v47 offset0:32 offset1:34
	v_cvt_pk_bf16_f32 v38, v18, v19
	v_cvt_pk_bf16_f32 v39, v20, v21
	v_cvt_pk_bf16_f32 v40, v22, v23
	v_cvt_pk_bf16_f32 v41, v24, v25
	ds_read2_b64 v[42:45], v47 offset0:36 offset1:38
	v_lshlrev_b32_e32 v48, 3, v51
	v_cvt_pk_bf16_f32 v72, v26, v27
	v_cvt_pk_bf16_f32 v73, v28, v29
	s_waitcnt lgkmcnt(1)
	v_mfma_f32_32x32x16_bf16 v[50:65], v[34:37], v[38:41], 0
	v_cvt_pk_bf16_f32 v74, v30, v31
	v_cvt_pk_bf16_f32 v75, v32, v33
	ds_read2_b64 v[34:37], v47 offset0:40 offset1:42
	v_cvt_pk_bf16_f32 v76, v2, v3
	v_cvt_pk_bf16_f32 v77, v4, v5
	v_cvt_pk_bf16_f32 v78, v6, v7
	v_cvt_pk_bf16_f32 v79, v8, v9
	s_waitcnt lgkmcnt(1)
	v_mfma_f32_32x32x16_bf16 v[50:65], v[42:45], v[72:75], v[50:65]
	ds_read2_b64 v[42:45], v47 offset0:44 offset1:46
	v_cvt_pk_bf16_f32 v172, v10, v11
	v_cvt_pk_bf16_f32 v173, v12, v13
	v_cvt_pk_bf16_f32 v174, v14, v15
	v_cvt_pk_bf16_f32 v175, v16, v17
	v_mov_b32_e32 v49, s92
	v_bitop3_b32 v47, v48, v141, 24 bitop3:0x78
	s_waitcnt lgkmcnt(1)
	v_mfma_f32_32x32x16_bf16 v[50:65], v[34:37], v[76:79], v[50:65]
	v_lshlrev_b32_e32 v34, 6, v70
	v_sub_u32_e32 v177, v66, v34
	v_lshl_add_u32 v70, v48, 1, v177
	ds_read_b128 v[34:37], v70 offset:50624
	v_mad_u32_u24 v49, v71, s77, v49
	v_lshlrev_b32_e32 v207, 1, v47
	v_and_b32_e32 v145, 24, v141
	s_waitcnt lgkmcnt(1)
	v_mfma_f32_32x32x16_bf16 v[50:65], v[42:45], v[172:175], v[50:65]
	v_add_u32_e32 v42, v49, v207
	ds_read_b128 v[130:133], v42 offset:45440
	v_bitop3_b32 v67, v48, v145, 16 bitop3:0x36
	v_lshlrev_b32_e32 v212, 1, v67
	v_add_u32_e32 v71, 0x5000, v46
	v_add_u32_e32 v47, v49, v212
	ds_read_b128 v[42:45], v70 offset:50656
	ds_read_b128 v[126:129], v47 offset:45440
	s_waitcnt lgkmcnt(2)
	v_mfma_f32_32x32x16_bf16 v[50:65], v[34:37], v[130:133], v[50:65]
	ds_read2_b64 v[34:37], v71 offset0:96 offset1:98
	ds_read2_b64 v[66:69], v71 offset0:100 offset1:102
	ds_read2_b64 v[178:181], v71 offset0:104 offset1:106
	ds_read2_b64 v[182:185], v71 offset0:108 offset1:110
	ds_read_b128 v[186:189], v70 offset:55744
	ds_read_b128 v[190:193], v70 offset:55776
	v_lshlrev_b32_e32 v81, 2, v0
	s_sub_i32 s58, s93, 32
	s_add_i32 s59, s94, 32
	s_and_b64 s[12:13], s[10:11], exec
	s_waitcnt lgkmcnt(6)
	v_mfma_f32_32x32x16_bf16 v[50:65], v[42:45], v[126:129], v[50:65]
	s_cselect_b32 s12, s58, s59
	s_add_i32 s12, s12, s87
	s_waitcnt lgkmcnt(5)
	v_mfma_f32_32x32x16_bf16 v[34:49], v[34:37], v[38:41], 0
	s_nop 7
	v_cvt_pk_bf16_f32 v50, v50, v51
	v_cvt_pk_bf16_f32 v51, v52, v53
	v_cvt_pk_bf16_f32 v52, v54, v55
	v_cvt_pk_bf16_f32 v53, v56, v57
	s_waitcnt lgkmcnt(4)
	v_mfma_f32_32x32x16_bf16 v[34:49], v[66:69], v[72:75], v[34:49]
	ds_read_b128 v[66:69], v81 offset:60928
	ds_read_b128 v[70:73], v81 offset:60960
	ds_read_b128 v[194:197], v81 offset:60864
	ds_read_b128 v[198:201], v81 offset:60896
	ds_read_b128 v[202:205], v81 offset:60992
	ds_read_b128 v[208:211], v81 offset:61024
	s_waitcnt lgkmcnt(4)
	v_pk_mul_f32 v[30:31], v[30:31], v[70:71]
	v_pk_mul_f32 v[26:27], v[26:27], v[66:67]
	v_pk_mul_f32 v[32:33], v[32:33], v[72:73]
	v_pk_mul_f32 v[28:29], v[28:29], v[68:69]
	ds_read_b128 v[66:69], v81 offset:61056
	ds_read_b128 v[70:73], v81 offset:61088
	s_waitcnt lgkmcnt(4)
	v_pk_mul_f32 v[22:23], v[22:23], v[198:199]
	v_mfma_f32_32x32x16_bf16 v[34:49], v[178:181], v[76:79], v[34:49]
	v_mul_f32_e64 v24, v24, v200
	v_mul_f32_e64 v25, v25, v201
	s_waitcnt lgkmcnt(1)
	v_mul_f32_e64 v10, v10, v66
	v_mul_f32_e64 v11, v11, v67
	s_waitcnt lgkmcnt(0)
	v_pk_mul_f32 v[14:15], v[14:15], v[70:71]
	v_pk_mul_f32 v[16:17], v[16:17], v[72:73]
	v_pk_mul_f32 v[12:13], v[12:13], v[68:69]
	v_pk_mul_f32 v[20:21], v[20:21], v[196:197]
	v_pk_mul_f32 v[18:19], v[18:19], v[194:195]
	v_mfma_f32_32x32x16_bf16 v[34:49], v[182:185], v[172:175], v[34:49]
	v_add_u32_e32 v172, v177, v80
	v_add_u32_e32 v66, 0xe000, v172
	ds_read2_b64 v[74:77], v66 offset0:120 offset1:122
	ds_read2_b64 v[54:57], v66 offset0:124 offset1:126
	v_mul_f32_e64 v6, v6, v208
	v_mul_f32_e64 v7, v7, v209
	v_pk_mul_f32 v[8:9], v[8:9], v[210:211]
	v_pk_mul_f32 v[4:5], v[4:5], v[204:205]
	s_waitcnt lgkmcnt(1)
	v_mfma_f32_32x32x16_bf16 v[66:81], v[74:77], v[50:53], 0
	v_cvt_pk_bf16_f32 v50, v58, v59
	v_cvt_pk_bf16_f32 v51, v60, v61
	v_cvt_pk_bf16_f32 v52, v62, v63
	v_cvt_pk_bf16_f32 v53, v64, v65
	v_add_u32_e32 v62, v177, v212
	v_pk_mul_f32 v[2:3], v[2:3], v[202:203]
	s_waitcnt lgkmcnt(0)
	v_mfma_f32_32x32x16_bf16 v[66:81], v[54:57], v[50:53], v[66:81]
	v_add_u32_e32 v54, v177, v207
	ds_read_b128 v[50:53], v54 offset:40256
	ds_read_b128 v[54:57], v54 offset:42880
	ds_read_b128 v[58:61], v62 offset:40256
	ds_read_b128 v[62:65], v62 offset:42880
	s_nop 6
	v_cvt_pk_bf16_f32 v66, v66, v67
	v_mfma_f32_32x32x16_bf16 v[34:49], v[186:189], v[130:133], v[34:49]
	v_cvt_pk_bf16_f32 v67, v68, v69
	v_cvt_pk_bf16_f32 v68, v70, v71
	v_cvt_pk_bf16_f32 v69, v72, v73
	v_cvt_pk_bf16_f32 v70, v74, v75
	v_cvt_pk_bf16_f32 v72, v78, v79
	v_add_u32_e32 v78, 0xc800, v172
	v_lshl_add_u32 v74, v145, 1, v172
	s_waitcnt lgkmcnt(3)
	v_mfma_f32_32x32x16_bf16 v[18:33], v[50:53], v[130:133], v[18:33]
	v_bitop3_b32 v50, v141, 8, 24 bitop3:0x6c
	v_lshl_add_u32 v75, v50, 1, v172
	v_bitop3_b32 v50, v141, 16, 24 bitop3:0x6c
	v_lshl_add_u32 v145, v50, 1, v172
	ds_read2_b64 v[50:53], v78 offset0:248 offset1:250
	v_cvt_pk_bf16_f32 v71, v76, v77
	v_cvt_pk_bf16_f32 v73, v80, v81
	v_mfma_f32_32x32x16_bf16 v[34:49], v[190:193], v[126:129], v[34:49]
	s_waitcnt lgkmcnt(0)
	v_mfma_f32_32x32x16_bf16 v[34:49], v[50:53], v[66:69], v[34:49]
	v_mfma_f32_32x32x16_bf16 v[18:33], v[58:61], v[126:129], v[18:33]
	v_bitop3_b32 v58, v141, 24, v141 bitop3:0xc
	v_lshl_add_u32 v141, v58, 1, v172
	ds_read_b64 v[58:59], v74 offset:35072
	ds_read_b64 v[60:61], v75 offset:35072
	ds_read_b64 v[76:77], v75 offset:37696
	ds_read_b64 v[74:75], v74 offset:37696
	ds_read2_b64 v[78:81], v78 offset0:252 offset1:254
	ds_read_b64 v[50:51], v145 offset:35072
	ds_read_b64 v[52:53], v141 offset:35072
	ds_read_b64 v[174:175], v141 offset:37696
	ds_read_b64 v[172:173], v145 offset:37696
	v_xor_b32_e32 v141, 31, v0
	v_cndmask_b32_e64 v141, v141, v0, s[10:11]
	v_mov_b32_e32 v145, v1
	s_waitcnt lgkmcnt(4)
	v_mfma_f32_32x32x16_bf16 v[34:49], v[78:81], v[70:73], v[34:49]
	v_or_b32_e32 v78, s12, v141
	v_ashrrev_i32_e32 v79, 31, v78
	v_lshl_add_u64 v[144:145], s[56:57], 0, v[144:145]
	v_lshlrev_b64 v[78:79], 12, v[78:79]
	v_lshl_add_u64 v[78:79], v[144:145], 0, v[78:79]
	s_and_b64 vcc, exec, s[10:11]
	s_cbranch_vccnz .Lys_fwd
	s_nop 6
	global_atomic_add_f32 v[78:79], v34, off
	v_xor_b32_e32 v34, 30, v0
	v_cndmask_b32_e64 v34, v34, v143, s[10:11]
	v_mfma_f32_32x32x16_bf16 v[2:17], v[54:57], v[130:133], v[2:17]
	v_or_b32_e32 v54, s12, v34
	v_ashrrev_i32_e32 v55, 31, v54
	v_xor_b32_e32 v34, 29, v0
	v_lshlrev_b64 v[54:55], 12, v[54:55]
	v_cndmask_b32_e64 v34, v34, v158, s[10:11]
	v_lshl_add_u64 v[54:55], v[144:145], 0, v[54:55]
	v_or_b32_e32 v34, s12, v34
	global_atomic_add_f32 v[54:55], v35, off
	v_ashrrev_i32_e32 v35, 31, v34
	v_lshlrev_b64 v[34:35], 12, v[34:35]
	v_lshl_add_u64 v[34:35], v[144:145], 0, v[34:35]
	global_atomic_add_f32 v[34:35], v36, off
	v_xor_b32_e32 v34, 28, v0
	v_cndmask_b32_e64 v34, v34, v159, s[10:11]
	v_or_b32_e32 v34, s12, v34
	v_ashrrev_i32_e32 v35, 31, v34
	v_lshlrev_b64 v[34:35], 12, v[34:35]
	v_lshl_add_u64 v[34:35], v[144:145], 0, v[34:35]
	global_atomic_add_f32 v[34:35], v37, off
	v_xor_b32_e32 v34, 23, v0
	v_cndmask_b32_e64 v34, v34, v160, s[10:11]
	v_or_b32_e32 v34, s12, v34
	v_ashrrev_i32_e32 v35, 31, v34
	v_lshlrev_b64 v[34:35], 12, v[34:35]
	v_lshl_add_u64 v[34:35], v[144:145], 0, v[34:35]
	global_atomic_add_f32 v[34:35], v38, off
	v_xor_b32_e32 v34, 22, v0
	v_cndmask_b32_e64 v34, v34, v161, s[10:11]
	v_or_b32_e32 v34, s12, v34
	v_ashrrev_i32_e32 v35, 31, v34
	v_lshlrev_b64 v[34:35], 12, v[34:35]
	v_lshl_add_u64 v[34:35], v[144:145], 0, v[34:35]
	global_atomic_add_f32 v[34:35], v39, off
	v_xor_b32_e32 v34, 21, v0
	v_cndmask_b32_e64 v34, v34, v162, s[10:11]
	v_or_b32_e32 v34, s12, v34
	v_ashrrev_i32_e32 v35, 31, v34
	v_lshlrev_b64 v[34:35], 12, v[34:35]
	v_lshl_add_u64 v[34:35], v[144:145], 0, v[34:35]
	global_atomic_add_f32 v[34:35], v40, off
	v_xor_b32_e32 v34, 20, v0
	v_cndmask_b32_e64 v34, v34, v163, s[10:11]
	v_or_b32_e32 v34, s12, v34
	v_ashrrev_i32_e32 v35, 31, v34
	v_lshlrev_b64 v[34:35], 12, v[34:35]
	v_lshl_add_u64 v[34:35], v[144:145], 0, v[34:35]
	global_atomic_add_f32 v[34:35], v41, off
	v_xor_b32_e32 v34, 15, v0
	v_cndmask_b32_e64 v34, v34, v164, s[10:11]
	v_or_b32_e32 v34, s12, v34
	v_ashrrev_i32_e32 v35, 31, v34
	v_lshlrev_b64 v[34:35], 12, v[34:35]
	v_lshl_add_u64 v[34:35], v[144:145], 0, v[34:35]
	global_atomic_add_f32 v[34:35], v42, off
	v_xor_b32_e32 v34, 14, v0
	v_cndmask_b32_e64 v34, v34, v165, s[10:11]
	v_or_b32_e32 v34, s12, v34
	v_ashrrev_i32_e32 v35, 31, v34
	v_lshlrev_b64 v[34:35], 12, v[34:35]
	v_lshl_add_u64 v[34:35], v[144:145], 0, v[34:35]
	global_atomic_add_f32 v[34:35], v43, off
	v_xor_b32_e32 v34, 13, v0
	v_cndmask_b32_e64 v34, v34, v166, s[10:11]
	v_or_b32_e32 v34, s12, v34
	v_ashrrev_i32_e32 v35, 31, v34
	v_lshlrev_b64 v[34:35], 12, v[34:35]
	v_lshl_add_u64 v[34:35], v[144:145], 0, v[34:35]
	global_atomic_add_f32 v[34:35], v44, off
	v_xor_b32_e32 v34, 12, v0
	v_cndmask_b32_e64 v34, v34, v167, s[10:11]
	v_or_b32_e32 v34, s12, v34
	v_ashrrev_i32_e32 v35, 31, v34
	v_lshlrev_b64 v[34:35], 12, v[34:35]
	v_lshl_add_u64 v[34:35], v[144:145], 0, v[34:35]
	global_atomic_add_f32 v[34:35], v45, off
	v_xor_b32_e32 v34, 7, v0
	v_cndmask_b32_e64 v34, v34, v168, s[10:11]
	v_or_b32_e32 v34, s12, v34
	v_ashrrev_i32_e32 v35, 31, v34
	v_lshlrev_b64 v[34:35], 12, v[34:35]
	v_lshl_add_u64 v[34:35], v[144:145], 0, v[34:35]
	global_atomic_add_f32 v[34:35], v46, off
	v_xor_b32_e32 v34, 6, v0
	v_cndmask_b32_e64 v34, v34, v169, s[10:11]
	v_or_b32_e32 v34, s12, v34
	v_ashrrev_i32_e32 v35, 31, v34
	v_lshlrev_b64 v[34:35], 12, v[34:35]
	v_lshl_add_u64 v[34:35], v[144:145], 0, v[34:35]
	global_atomic_add_f32 v[34:35], v47, off
	v_xor_b32_e32 v34, 5, v0
	v_cndmask_b32_e64 v34, v34, v170, s[10:11]
	v_or_b32_e32 v34, s12, v34
	v_ashrrev_i32_e32 v35, 31, v34
	v_lshlrev_b64 v[34:35], 12, v[34:35]
	v_xor_b32_e32 v0, 4, v0
	v_lshl_add_u64 v[34:35], v[144:145], 0, v[34:35]
	v_cndmask_b32_e64 v0, v0, v171, s[10:11]
	global_atomic_add_f32 v[34:35], v48, off
	v_or_b32_e32 v34, s12, v0
	v_ashrrev_i32_e32 v35, 31, v34
	v_lshlrev_b64 v[34:35], 12, v[34:35]
	v_lshl_add_u64 v[34:35], v[144:145], 0, v[34:35]
	global_atomic_add_f32 v[34:35], v49, off
	s_branch .Lys_join
.Lys_fwd:
	s_nop 6
	global_store_dword v[78:79], v34, off
	v_xor_b32_e32 v34, 30, v0
	v_cndmask_b32_e64 v34, v34, v143, s[10:11]
	v_mfma_f32_32x32x16_bf16 v[2:17], v[54:57], v[130:133], v[2:17]
	v_or_b32_e32 v54, s12, v34
	v_ashrrev_i32_e32 v55, 31, v54
	v_xor_b32_e32 v34, 29, v0
	v_lshlrev_b64 v[54:55], 12, v[54:55]
	v_cndmask_b32_e64 v34, v34, v158, s[10:11]
	v_lshl_add_u64 v[54:55], v[144:145], 0, v[54:55]
	v_or_b32_e32 v34, s12, v34
	global_store_dword v[54:55], v35, off
	v_ashrrev_i32_e32 v35, 31, v34
	v_lshlrev_b64 v[34:35], 12, v[34:35]
	v_lshl_add_u64 v[34:35], v[144:145], 0, v[34:35]
	global_store_dword v[34:35], v36, off
	v_xor_b32_e32 v34, 28, v0
	v_cndmask_b32_e64 v34, v34, v159, s[10:11]
	v_or_b32_e32 v34, s12, v34
	v_ashrrev_i32_e32 v35, 31, v34
	v_lshlrev_b64 v[34:35], 12, v[34:35]
	v_lshl_add_u64 v[34:35], v[144:145], 0, v[34:35]
	global_store_dword v[34:35], v37, off
	v_xor_b32_e32 v34, 23, v0
	v_cndmask_b32_e64 v34, v34, v160, s[10:11]
	v_or_b32_e32 v34, s12, v34
	v_ashrrev_i32_e32 v35, 31, v34
	v_lshlrev_b64 v[34:35], 12, v[34:35]
	v_lshl_add_u64 v[34:35], v[144:145], 0, v[34:35]
	global_store_dword v[34:35], v38, off
	v_xor_b32_e32 v34, 22, v0
	v_cndmask_b32_e64 v34, v34, v161, s[10:11]
	v_or_b32_e32 v34, s12, v34
	v_ashrrev_i32_e32 v35, 31, v34
	v_lshlrev_b64 v[34:35], 12, v[34:35]
	v_lshl_add_u64 v[34:35], v[144:145], 0, v[34:35]
	global_store_dword v[34:35], v39, off
	v_xor_b32_e32 v34, 21, v0
	v_cndmask_b32_e64 v34, v34, v162, s[10:11]
	v_or_b32_e32 v34, s12, v34
	v_ashrrev_i32_e32 v35, 31, v34
	v_lshlrev_b64 v[34:35], 12, v[34:35]
	v_lshl_add_u64 v[34:35], v[144:145], 0, v[34:35]
	global_store_dword v[34:35], v40, off
	v_xor_b32_e32 v34, 20, v0
	v_cndmask_b32_e64 v34, v34, v163, s[10:11]
	v_or_b32_e32 v34, s12, v34
	v_ashrrev_i32_e32 v35, 31, v34
	v_lshlrev_b64 v[34:35], 12, v[34:35]
	v_lshl_add_u64 v[34:35], v[144:145], 0, v[34:35]
	global_store_dword v[34:35], v41, off
	v_xor_b32_e32 v34, 15, v0
	v_cndmask_b32_e64 v34, v34, v164, s[10:11]
	v_or_b32_e32 v34, s12, v34
	v_ashrrev_i32_e32 v35, 31, v34
	v_lshlrev_b64 v[34:35], 12, v[34:35]
	v_lshl_add_u64 v[34:35], v[144:145], 0, v[34:35]
	global_store_dword v[34:35], v42, off
	v_xor_b32_e32 v34, 14, v0
	v_cndmask_b32_e64 v34, v34, v165, s[10:11]
	v_or_b32_e32 v34, s12, v34
	v_ashrrev_i32_e32 v35, 31, v34
	v_lshlrev_b64 v[34:35], 12, v[34:35]
	v_lshl_add_u64 v[34:35], v[144:145], 0, v[34:35]
	global_store_dword v[34:35], v43, off
	v_xor_b32_e32 v34, 13, v0
	v_cndmask_b32_e64 v34, v34, v166, s[10:11]
	v_or_b32_e32 v34, s12, v34
	v_ashrrev_i32_e32 v35, 31, v34
	v_lshlrev_b64 v[34:35], 12, v[34:35]
	v_lshl_add_u64 v[34:35], v[144:145], 0, v[34:35]
	global_store_dword v[34:35], v44, off
	v_xor_b32_e32 v34, 12, v0
	v_cndmask_b32_e64 v34, v34, v167, s[10:11]
	v_or_b32_e32 v34, s12, v34
	v_ashrrev_i32_e32 v35, 31, v34
	v_lshlrev_b64 v[34:35], 12, v[34:35]
	v_lshl_add_u64 v[34:35], v[144:145], 0, v[34:35]
	global_store_dword v[34:35], v45, off
	v_xor_b32_e32 v34, 7, v0
	v_cndmask_b32_e64 v34, v34, v168, s[10:11]
	v_or_b32_e32 v34, s12, v34
	v_ashrrev_i32_e32 v35, 31, v34
	v_lshlrev_b64 v[34:35], 12, v[34:35]
	v_lshl_add_u64 v[34:35], v[144:145], 0, v[34:35]
	global_store_dword v[34:35], v46, off
	v_xor_b32_e32 v34, 6, v0
	v_cndmask_b32_e64 v34, v34, v169, s[10:11]
	v_or_b32_e32 v34, s12, v34
	v_ashrrev_i32_e32 v35, 31, v34
	v_lshlrev_b64 v[34:35], 12, v[34:35]
	v_lshl_add_u64 v[34:35], v[144:145], 0, v[34:35]
	global_store_dword v[34:35], v47, off
	v_xor_b32_e32 v34, 5, v0
	v_cndmask_b32_e64 v34, v34, v170, s[10:11]
	v_or_b32_e32 v34, s12, v34
	v_ashrrev_i32_e32 v35, 31, v34
	v_lshlrev_b64 v[34:35], 12, v[34:35]
	v_xor_b32_e32 v0, 4, v0
	v_lshl_add_u64 v[34:35], v[144:145], 0, v[34:35]
	v_cndmask_b32_e64 v0, v0, v171, s[10:11]
	global_store_dword v[34:35], v48, off
	v_or_b32_e32 v34, s12, v0
	v_ashrrev_i32_e32 v35, 31, v34
	v_lshlrev_b64 v[34:35], 12, v[34:35]
	v_lshl_add_u64 v[34:35], v[144:145], 0, v[34:35]
	global_store_dword v[34:35], v49, off
.Lys_join:
	v_mfma_f32_32x32x16_bf16 v[2:17], v[62:65], v[126:129], v[2:17]
	v_mfma_f32_32x32x16_bf16 v[18:33], v[58:61], v[66:69], v[18:33]
	v_mfma_f32_32x32x16_bf16 v[2:17], v[74:77], v[66:69], v[2:17]
	s_waitcnt lgkmcnt(2)
	v_mfma_f32_32x32x16_bf16 v[18:33], v[50:53], v[70:73], v[18:33]
	s_waitcnt lgkmcnt(0)
	v_mfma_f32_32x32x16_bf16 v[2:17], v[172:175], v[70:73], v[2:17]
	s_branch .LBB0_1106
